# P2 stage F: static weight-conversion tickets (4*item+wave) instead of a hot-counter atomic; counter starts at 4096
# speedup vs baseline: 1.0091x; 1.0051x over previous
.LBB0_89:
	v_or_b32_e32 v0, s2, v6
	v_cmp_eq_u32_e32 vcc, 0, v0
	s_and_saveexec_b64 s[0:1], vcc
	s_cbranch_execz .LBB0_91
	v_mov_b32_e32 v0, 0x17feb000
	v_mov_b32_e32 v1, 0
	v_mov_b32_e32 v2, 0x1000
	global_store_dword v0, v2, s[30:31]
	global_store_dword v0, v1, s[30:31] offset:128
	global_store_dword v0, v1, s[30:31] offset:192

.LBB0_360:
	s_or_b64 exec, exec, s[4:5]
	s_waitcnt lgkmcnt(0)
	s_barrier
	s_and_saveexec_b64 s[4:5], s[44:45]
	s_xor_b64 s[4:5], exec, s[4:5]
	s_cbranch_execz .LBB0_373
	ds_read_b32 v16, v131
	v_lshl_add_u64 v[0:1], s[96:97], 0, v[76:77]
	v_lshl_add_u64 v[18:19], v[0:1], 0, v[78:79]
	ds_read_b128 v[0:3], v183
	ds_read_b128 v[4:7], v183 offset:16
	ds_read_b128 v[8:11], v183 offset:32
	ds_read_b128 v[12:15], v183 offset:48
	s_mov_b64 s[6:7], 0x4400
	s_waitcnt lgkmcnt(3)
	v_lshlrev_b32_e32 v22, 16, v0
	v_and_b32_e32 v23, 0xffff0000, v0
	v_pk_mul_f32 v[22:23], v[16:17], v[22:23] op_sel_hi:[0,1]
	v_cvt_pk_bf16_f32 v0, v22, v23
	v_lshlrev_b32_e32 v22, 16, v1
	v_and_b32_e32 v23, 0xffff0000, v1
	v_pk_mul_f32 v[22:23], v[16:17], v[22:23] op_sel_hi:[0,1]
	v_cvt_pk_bf16_f32 v1, v22, v23
	v_lshlrev_b32_e32 v22, 16, v2
	v_and_b32_e32 v23, 0xffff0000, v2
	v_pk_mul_f32 v[22:23], v[16:17], v[22:23] op_sel_hi:[0,1]
	v_lshl_add_u64 v[20:21], v[18:19], 0, s[6:7]
	v_cvt_pk_bf16_f32 v2, v22, v23
	v_lshlrev_b32_e32 v22, 16, v3
	v_and_b32_e32 v23, 0xffff0000, v3
	s_movk_i32 s6, 0x4000
	v_pk_mul_f32 v[22:23], v[16:17], v[22:23] op_sel_hi:[0,1]
	v_add_co_u32_e32 v18, vcc, s6, v18
	v_cvt_pk_bf16_f32 v3, v22, v23
	s_nop 0
	v_addc_co_u32_e32 v19, vcc, 0, v19, vcc
	global_store_dwordx4 v[18:19], v[0:3], off offset:1024
	s_mov_b64 s[6:7], 0xac00
	s_waitcnt lgkmcnt(2)
	v_lshlrev_b32_e32 v0, 16, v4
	v_and_b32_e32 v1, 0xffff0000, v4
	v_lshlrev_b32_e32 v2, 16, v5
	v_and_b32_e32 v3, 0xffff0000, v5
	v_pk_mul_f32 v[0:1], v[16:17], v[0:1] op_sel_hi:[0,1]
	v_pk_mul_f32 v[2:3], v[16:17], v[2:3] op_sel_hi:[0,1]
	v_cvt_pk_bf16_f32 v0, v0, v1
	v_cvt_pk_bf16_f32 v1, v2, v3
	v_lshlrev_b32_e32 v2, 16, v6
	v_and_b32_e32 v3, 0xffff0000, v6
	v_lshlrev_b32_e32 v4, 16, v7
	v_and_b32_e32 v5, 0xffff0000, v7
	v_pk_mul_f32 v[2:3], v[16:17], v[2:3] op_sel_hi:[0,1]
	v_pk_mul_f32 v[4:5], v[16:17], v[4:5] op_sel_hi:[0,1]
	v_cvt_pk_bf16_f32 v2, v2, v3
	v_cvt_pk_bf16_f32 v3, v4, v5
	global_store_dwordx4 v[20:21], v[0:3], off offset:16
	s_waitcnt lgkmcnt(1)
	v_lshlrev_b32_e32 v4, 16, v11
	v_and_b32_e32 v5, 0xffff0000, v11
	v_lshlrev_b32_e32 v0, 16, v8
	v_and_b32_e32 v1, 0xffff0000, v8
	v_lshlrev_b32_e32 v2, 16, v9
	v_and_b32_e32 v3, 0xffff0000, v9
	v_pk_mul_f32 v[0:1], v[16:17], v[0:1] op_sel_hi:[0,1]
	v_pk_mul_f32 v[2:3], v[16:17], v[2:3] op_sel_hi:[0,1]
	v_cvt_pk_bf16_f32 v0, v0, v1
	v_cvt_pk_bf16_f32 v1, v2, v3
	v_lshlrev_b32_e32 v2, 16, v10
	v_and_b32_e32 v3, 0xffff0000, v10
	v_pk_mul_f32 v[2:3], v[16:17], v[2:3] op_sel_hi:[0,1]
	v_pk_mul_f32 v[4:5], v[16:17], v[4:5] op_sel_hi:[0,1]
	v_cvt_pk_bf16_f32 v2, v2, v3
	v_cvt_pk_bf16_f32 v3, v4, v5
	global_store_dwordx4 v[20:21], v[0:3], off offset:32
	s_waitcnt lgkmcnt(0)
	v_lshlrev_b32_e32 v4, 16, v15
	v_and_b32_e32 v5, 0xffff0000, v15
	v_lshlrev_b32_e32 v0, 16, v12
	v_and_b32_e32 v1, 0xffff0000, v12
	v_lshlrev_b32_e32 v2, 16, v13
	v_and_b32_e32 v3, 0xffff0000, v13
	v_pk_mul_f32 v[0:1], v[16:17], v[0:1] op_sel_hi:[0,1]
	v_pk_mul_f32 v[2:3], v[16:17], v[2:3] op_sel_hi:[0,1]
	v_cvt_pk_bf16_f32 v0, v0, v1
	v_cvt_pk_bf16_f32 v1, v2, v3
	v_lshlrev_b32_e32 v2, 16, v14
	v_and_b32_e32 v3, 0xffff0000, v14
	v_pk_mul_f32 v[2:3], v[16:17], v[2:3] op_sel_hi:[0,1]
	v_pk_mul_f32 v[4:5], v[16:17], v[4:5] op_sel_hi:[0,1]
	v_cvt_pk_bf16_f32 v2, v2, v3
	v_cvt_pk_bf16_f32 v3, v4, v5
	global_store_dwordx4 v[20:21], v[0:3], off offset:48
	s_nop 1
	v_lshl_add_u64 v[0:1], s[96:97], 0, v[82:83]
	v_lshl_add_u64 v[6:7], v[0:1], 0, v[84:85]
	v_lshl_add_u64 v[4:5], v[6:7], 0, s[6:7]
	s_mov_b32 s6, 0xa000
	v_add_co_u32_e32 v6, vcc, s6, v6
	s_nop 1
	v_addc_co_u32_e32 v7, vcc, 0, v7, vcc
	ds_read_u16 v240, v172
	ds_read_u16 v241, v172 offset:272
	ds_read_u16 v242, v173
	ds_read_u16 v243, v172 offset:816
	ds_read_u16 v244, v173 offset:544
	ds_read_u16 v245, v172 offset:1360
	ds_read_u16 v246, v173 offset:1088
	ds_read_u16 v247, v172 offset:1904
	ds_read_b128 v[248:251], v157
	ds_read_b128 v[20:23], v158
	s_waitcnt lgkmcnt(0)
	v_lshlrev_b32_e32 v8, 16, v240
	v_lshlrev_b32_e32 v9, 16, v241
	v_lshlrev_b32_e32 v10, 16, v242
	v_lshlrev_b32_e32 v11, 16, v243
	v_lshlrev_b32_e32 v12, 16, v244
	v_lshlrev_b32_e32 v13, 16, v245
	v_lshlrev_b32_e32 v14, 16, v246
	v_lshlrev_b32_e32 v15, 16, v247
	v_pk_mul_f32 v[8:9], v[248:249], v[8:9]
	v_pk_mul_f32 v[10:11], v[250:251], v[10:11]
	v_pk_mul_f32 v[12:13], v[20:21], v[12:13]
	v_pk_mul_f32 v[14:15], v[22:23], v[14:15]
	ds_read_u16 v240, v173 offset:1632
	ds_read_u16 v241, v172 offset:2448
	ds_read_u16 v242, v173 offset:2176
	ds_read_u16 v243, v172 offset:2992
	ds_read_u16 v244, v173 offset:2720
	ds_read_u16 v245, v172 offset:3536
	ds_read_u16 v246, v173 offset:3264
	ds_read_u16 v247, v172 offset:4080
	ds_read_b128 v[248:251], v159
	ds_read_b128 v[20:23], v160
	v_cvt_pk_bf16_f32 v0, v8, v9
	v_cvt_pk_bf16_f32 v1, v10, v11
	v_cvt_pk_bf16_f32 v2, v12, v13
	v_cvt_pk_bf16_f32 v3, v14, v15
	global_store_dwordx4 v[6:7], v[0:3], off offset:3072
	s_waitcnt lgkmcnt(0)
	v_lshlrev_b32_e32 v8, 16, v240
	v_lshlrev_b32_e32 v9, 16, v241
	v_lshlrev_b32_e32 v10, 16, v242
	v_lshlrev_b32_e32 v11, 16, v243
	v_lshlrev_b32_e32 v12, 16, v244
	v_lshlrev_b32_e32 v13, 16, v245
	v_lshlrev_b32_e32 v14, 16, v246
	v_lshlrev_b32_e32 v15, 16, v247
	v_pk_mul_f32 v[8:9], v[248:249], v[8:9]
	v_pk_mul_f32 v[10:11], v[250:251], v[10:11]
	v_pk_mul_f32 v[12:13], v[20:21], v[12:13]
	v_pk_mul_f32 v[14:15], v[22:23], v[14:15]
	ds_read_u16 v240, v173 offset:3808
	ds_read_u16 v241, v172 offset:4624
	ds_read_u16 v242, v173 offset:4352
	ds_read_u16 v243, v172 offset:5168
	ds_read_u16 v244, v173 offset:4896
	ds_read_u16 v245, v172 offset:5712
	ds_read_u16 v246, v173 offset:5440
	ds_read_u16 v247, v172 offset:6256
	ds_read_b128 v[248:251], v161
	ds_read_b128 v[20:23], v162
	v_cvt_pk_bf16_f32 v0, v8, v9
	v_cvt_pk_bf16_f32 v1, v10, v11
	v_cvt_pk_bf16_f32 v2, v12, v13
	v_cvt_pk_bf16_f32 v3, v14, v15
	global_store_dwordx4 v[4:5], v[0:3], off offset:16
	s_waitcnt lgkmcnt(0)
	v_lshlrev_b32_e32 v8, 16, v240
	v_lshlrev_b32_e32 v9, 16, v241
	v_lshlrev_b32_e32 v10, 16, v242
	v_lshlrev_b32_e32 v11, 16, v243
	v_lshlrev_b32_e32 v12, 16, v244
	v_lshlrev_b32_e32 v13, 16, v245
	v_lshlrev_b32_e32 v14, 16, v246
	v_lshlrev_b32_e32 v15, 16, v247
	v_pk_mul_f32 v[8:9], v[248:249], v[8:9]
	v_pk_mul_f32 v[10:11], v[250:251], v[10:11]
	v_pk_mul_f32 v[12:13], v[20:21], v[12:13]
	v_pk_mul_f32 v[14:15], v[22:23], v[14:15]
	ds_read_u16 v240, v173 offset:5984
	ds_read_u16 v241, v172 offset:6800
	ds_read_u16 v242, v173 offset:6528
	ds_read_u16 v243, v172 offset:7344
	ds_read_u16 v244, v173 offset:7072
	ds_read_u16 v245, v172 offset:7888
	ds_read_u16 v246, v173 offset:7616
	ds_read_u16 v247, v172 offset:8432
	ds_read_b128 v[248:251], v163
	ds_read_b128 v[20:23], v164
	v_cvt_pk_bf16_f32 v0, v8, v9
	v_cvt_pk_bf16_f32 v1, v10, v11
	v_cvt_pk_bf16_f32 v2, v12, v13
	v_cvt_pk_bf16_f32 v3, v14, v15
	global_store_dwordx4 v[4:5], v[0:3], off offset:32
	s_waitcnt lgkmcnt(0)
	v_lshlrev_b32_e32 v8, 16, v240
	v_lshlrev_b32_e32 v9, 16, v241
	v_lshlrev_b32_e32 v10, 16, v242
	v_lshlrev_b32_e32 v11, 16, v243
	v_lshlrev_b32_e32 v12, 16, v244
	v_lshlrev_b32_e32 v13, 16, v245
	v_lshlrev_b32_e32 v14, 16, v246
	v_lshlrev_b32_e32 v15, 16, v247
	v_pk_mul_f32 v[8:9], v[248:249], v[8:9]
	v_pk_mul_f32 v[10:11], v[250:251], v[10:11]
	v_pk_mul_f32 v[12:13], v[20:21], v[12:13]
	v_pk_mul_f32 v[14:15], v[22:23], v[14:15]
	v_cvt_pk_bf16_f32 v0, v8, v9
	v_cvt_pk_bf16_f32 v1, v10, v11
	v_cvt_pk_bf16_f32 v2, v12, v13
	v_cvt_pk_bf16_f32 v3, v14, v15
	global_store_dwordx4 v[4:5], v[0:3], off offset:48
	v_readfirstlane_b32 s8, v176
	s_lshr_b32 s8, s8, 6
	s_add_i32 s8, s8, -4
	s_lshl_b32 s9, s12, 2
	s_add_i32 s8, s8, s9
	s_cmpk_gt_i32 s8, 0x20ff
	s_cbranch_scc1 .LBB0_373
	s_cmpk_gt_i32 s8, 0x15ff
	s_mov_b64 s[6:7], -1
	s_cbranch_scc0 .LBB0_368
	s_add_i32 s6, s8, 0xea00
	s_and_b32 s7, s6, 0xffff
	s_mul_i32 s7, s7, 0xba2f
	s_lshr_b32 s9, s7, 16
	s_lshr_b32 s7, s7, 22
	s_mulk_i32 s7, 0x58
	s_sub_i32 s6, s6, s7
	s_and_b32 s7, s9, 0xffc0
	v_or_b32_e32 v2, s7, v121
	v_readlane_b32 s10, v238, 23
	s_lshl_b32 s6, s6, 6
	v_mul_u32_u24_e32 v80, 0x2c00, v2
	v_readlane_b32 s11, v238, 24
	s_and_b32 s6, s6, 0xffc0
	s_lshl_b32 s50, s6, 1
	v_lshl_add_u64 v[0:1], s[10:11], 0, v[80:81]
	v_lshlrev_b32_e32 v80, 2, v2
	v_lshl_add_u64 v[38:39], v[0:1], 0, s[50:51]
	v_lshl_add_u64 v[0:1], s[60:61], 0, v[80:81]
	s_lshl_b32 s50, s6, 13
	v_lshl_add_u64 v[40:41], v[0:1], 0, s[50:51]
	s_movk_i32 s6, 0x2000
	v_add_co_u32_e32 v0, vcc, s6, v40
	s_movk_i32 s6, 0x4000
	s_nop 0
	v_addc_co_u32_e32 v1, vcc, 0, v41, vcc
	global_load_dword v44, v[40:41], off nt
	global_load_dword v45, v[0:1], off nt
	v_add_co_u32_e32 v0, vcc, s6, v40
	s_movk_i32 s6, 0x6000
	s_nop 0
	v_addc_co_u32_e32 v1, vcc, 0, v41, vcc
	global_load_dword v46, v[0:1], off nt
	v_add_co_u32_e32 v0, vcc, s6, v40
	s_mov_b32 s6, 0x8000
	s_nop 0
	v_addc_co_u32_e32 v1, vcc, 0, v41, vcc
	global_load_dword v47, v[0:1], off nt
	v_add_co_u32_e32 v0, vcc, s6, v40
	s_mov_b32 s6, 0xa000
	s_nop 0
	v_addc_co_u32_e32 v1, vcc, 0, v41, vcc
	global_load_dword v48, v[0:1], off nt
	v_add_co_u32_e32 v0, vcc, s6, v40
	s_mov_b32 s6, 0xc000
	s_nop 0
	v_addc_co_u32_e32 v1, vcc, 0, v41, vcc
	global_load_dword v49, v[0:1], off nt
	v_add_co_u32_e32 v0, vcc, s6, v40
	s_mov_b32 s6, 0xe000
	s_nop 0
	v_addc_co_u32_e32 v1, vcc, 0, v41, vcc
	global_load_dword v66, v[0:1], off nt
	v_add_co_u32_e32 v0, vcc, s6, v40
	s_mov_b32 s6, 0x10000
	s_nop 0
	v_addc_co_u32_e32 v1, vcc, 0, v41, vcc
	global_load_dword v67, v[0:1], off nt
	v_add_co_u32_e32 v0, vcc, s6, v40
	s_mov_b32 s6, 0x12000
	s_nop 0
	v_addc_co_u32_e32 v1, vcc, 0, v41, vcc
	v_add_co_u32_e32 v2, vcc, s6, v40
	s_mov_b32 s6, 0x14000
	s_nop 0
	v_addc_co_u32_e32 v3, vcc, 0, v41, vcc
	global_load_dword v0, v[0:1], off nt
	s_waitcnt vmcnt(7)
	v_cvt_pk_bf16_f32 v44, v44, v45
	global_load_dword v1, v[2:3], off nt
	v_add_co_u32_e32 v2, vcc, s6, v40
	s_mov_b32 s6, 0x16000
	s_nop 0
	v_addc_co_u32_e32 v3, vcc, 0, v41, vcc
	v_add_co_u32_e32 v4, vcc, s6, v40
	s_mov_b32 s6, 0x18000
	s_nop 0
	v_addc_co_u32_e32 v5, vcc, 0, v41, vcc
	global_load_dword v2, v[2:3], off nt
	s_waitcnt vmcnt(7)
	v_cvt_pk_bf16_f32 v45, v46, v47
	global_load_dword v3, v[4:5], off nt
	v_add_co_u32_e32 v4, vcc, s6, v40
	s_mov_b32 s6, 0x1a000
	s_nop 0
	v_addc_co_u32_e32 v5, vcc, 0, v41, vcc
	v_add_co_u32_e32 v6, vcc, s6, v40
	s_mov_b32 s6, 0x1c000
	s_nop 0
	v_addc_co_u32_e32 v7, vcc, 0, v41, vcc
	global_load_dword v4, v[4:5], off nt
	s_waitcnt vmcnt(7)
	v_cvt_pk_bf16_f32 v46, v48, v49
	global_load_dword v5, v[6:7], off nt
	v_add_co_u32_e32 v6, vcc, s6, v40
	s_mov_b32 s6, 0x1e000
	s_nop 0
	v_addc_co_u32_e32 v7, vcc, 0, v41, vcc
	v_add_co_u32_e32 v8, vcc, s6, v40
	s_mov_b32 s6, 0x20000
	s_nop 0
	v_addc_co_u32_e32 v9, vcc, 0, v41, vcc
	global_load_dword v6, v[6:7], off nt
	s_waitcnt vmcnt(7)
	v_cvt_pk_bf16_f32 v47, v66, v67
	global_load_dword v7, v[8:9], off nt
	v_add_co_u32_e32 v8, vcc, s6, v40
	s_mov_b32 s6, 0x22000
	s_nop 0
	v_addc_co_u32_e32 v9, vcc, 0, v41, vcc
	v_add_co_u32_e32 v10, vcc, s6, v40
	s_mov_b32 s6, 0x24000
	s_nop 0
	v_addc_co_u32_e32 v11, vcc, 0, v41, vcc
	global_load_dword v8, v[8:9], off nt
	s_nop 0
	global_load_dword v9, v[10:11], off nt
	v_add_co_u32_e32 v10, vcc, s6, v40
	s_mov_b32 s6, 0x26000
	s_nop 0
	v_addc_co_u32_e32 v11, vcc, 0, v41, vcc
	v_add_co_u32_e32 v12, vcc, s6, v40
	s_mov_b32 s6, 0x28000
	s_nop 0
	v_addc_co_u32_e32 v13, vcc, 0, v41, vcc
	global_load_dword v10, v[10:11], off nt
	s_nop 0
	global_load_dword v11, v[12:13], off nt
	v_add_co_u32_e32 v12, vcc, s6, v40
	s_mov_b32 s6, 0x2a000
	s_nop 0
	v_addc_co_u32_e32 v13, vcc, 0, v41, vcc
	v_add_co_u32_e32 v14, vcc, s6, v40
	s_mov_b32 s6, 0x2c000
	s_nop 0
	v_addc_co_u32_e32 v15, vcc, 0, v41, vcc
	global_load_dword v12, v[12:13], off nt
	s_nop 0
	global_load_dword v13, v[14:15], off nt
	v_add_co_u32_e32 v14, vcc, s6, v40
	s_mov_b32 s6, 0x2e000
	s_nop 0
	v_addc_co_u32_e32 v15, vcc, 0, v41, vcc
	v_add_co_u32_e32 v16, vcc, s6, v40
	s_mov_b32 s6, 0x30000
	s_nop 0
	v_addc_co_u32_e32 v17, vcc, 0, v41, vcc
	global_load_dword v14, v[14:15], off nt
	s_nop 0
	global_load_dword v15, v[16:17], off nt
	v_add_co_u32_e32 v16, vcc, s6, v40
	s_mov_b32 s6, 0x32000
	s_nop 0
	v_addc_co_u32_e32 v17, vcc, 0, v41, vcc
	v_add_co_u32_e32 v18, vcc, s6, v40
	s_mov_b32 s6, 0x34000
	s_nop 0
	v_addc_co_u32_e32 v19, vcc, 0, v41, vcc
	global_load_dword v16, v[16:17], off nt
	s_nop 0
	global_load_dword v17, v[18:19], off nt
	v_add_co_u32_e32 v18, vcc, s6, v40
	s_mov_b32 s6, 0x36000
	s_nop 0
	v_addc_co_u32_e32 v19, vcc, 0, v41, vcc
	v_add_co_u32_e32 v20, vcc, s6, v40
	s_mov_b32 s6, 0x38000
	s_nop 0
	v_addc_co_u32_e32 v21, vcc, 0, v41, vcc
	global_load_dword v18, v[18:19], off nt
	s_nop 0
	global_load_dword v19, v[20:21], off nt
	v_add_co_u32_e32 v20, vcc, s6, v40
	s_mov_b32 s6, 0x3a000
	s_nop 0
	v_addc_co_u32_e32 v21, vcc, 0, v41, vcc
	v_add_co_u32_e32 v22, vcc, s6, v40
	s_mov_b32 s6, 0x3c000
	s_nop 0
	v_addc_co_u32_e32 v23, vcc, 0, v41, vcc
	global_load_dword v20, v[20:21], off nt
	s_nop 0
	global_load_dword v21, v[22:23], off nt
	v_add_co_u32_e32 v22, vcc, s6, v40
	s_mov_b32 s6, 0x3e000
	s_nop 0
	v_addc_co_u32_e32 v23, vcc, 0, v41, vcc
	v_add_co_u32_e32 v24, vcc, s6, v40
	s_mov_b32 s6, 0x40000
	s_nop 0
	v_addc_co_u32_e32 v25, vcc, 0, v41, vcc
	global_load_dword v22, v[22:23], off nt
	s_nop 0
	global_load_dword v23, v[24:25], off nt
	v_add_co_u32_e32 v24, vcc, s6, v40
	s_mov_b32 s6, 0x42000
	s_nop 0
	v_addc_co_u32_e32 v25, vcc, 0, v41, vcc
	v_add_co_u32_e32 v26, vcc, s6, v40
	s_mov_b32 s6, 0x44000
	s_nop 0
	v_addc_co_u32_e32 v27, vcc, 0, v41, vcc
	global_load_dword v24, v[24:25], off nt
	s_nop 0
	global_load_dword v25, v[26:27], off nt
	v_add_co_u32_e32 v26, vcc, s6, v40
	s_mov_b32 s6, 0x46000
	s_nop 0
	v_addc_co_u32_e32 v27, vcc, 0, v41, vcc
	v_add_co_u32_e32 v28, vcc, s6, v40
	s_mov_b32 s6, 0x48000
	s_nop 0
	v_addc_co_u32_e32 v29, vcc, 0, v41, vcc
	global_load_dword v26, v[26:27], off nt
	s_nop 0
	global_load_dword v27, v[28:29], off nt
	v_add_co_u32_e32 v28, vcc, s6, v40
	s_mov_b32 s6, 0x4a000
	s_nop 0
	v_addc_co_u32_e32 v29, vcc, 0, v41, vcc
	v_add_co_u32_e32 v30, vcc, s6, v40
	s_mov_b32 s6, 0x4c000
	s_nop 0
	v_addc_co_u32_e32 v31, vcc, 0, v41, vcc
	global_load_dword v28, v[28:29], off nt
	s_nop 0
	global_load_dword v29, v[30:31], off nt
	v_add_co_u32_e32 v30, vcc, s6, v40
	s_mov_b32 s6, 0x4e000
	s_nop 0
	v_addc_co_u32_e32 v31, vcc, 0, v41, vcc
	v_add_co_u32_e32 v32, vcc, s6, v40
	s_mov_b32 s6, 0x50000
	s_nop 0
	v_addc_co_u32_e32 v33, vcc, 0, v41, vcc
	global_load_dword v30, v[30:31], off nt
	s_nop 0
	global_load_dword v31, v[32:33], off nt
	v_add_co_u32_e32 v32, vcc, s6, v40
	s_mov_b32 s6, 0x52000
	s_nop 0
	v_addc_co_u32_e32 v33, vcc, 0, v41, vcc
	v_add_co_u32_e32 v34, vcc, s6, v40
	s_mov_b32 s6, 0x54000
	s_nop 0
	v_addc_co_u32_e32 v35, vcc, 0, v41, vcc
	global_load_dword v32, v[32:33], off nt
	s_nop 0
	global_load_dword v33, v[34:35], off nt
	v_add_co_u32_e32 v34, vcc, s6, v40
	s_mov_b32 s6, 0x56000
	s_nop 0
	v_addc_co_u32_e32 v35, vcc, 0, v41, vcc
	v_add_co_u32_e32 v36, vcc, s6, v40
	s_mov_b32 s6, 0x58000
	s_nop 0
	v_addc_co_u32_e32 v37, vcc, 0, v41, vcc
	global_load_dword v34, v[34:35], off nt
	s_nop 0
	global_load_dword v35, v[36:37], off nt
	v_add_co_u32_e32 v36, vcc, s6, v40
	s_mov_b32 s6, 0x5a000
	s_nop 0
	v_addc_co_u32_e32 v37, vcc, 0, v41, vcc
	v_add_co_u32_e32 v42, vcc, s6, v40
	s_mov_b32 s6, 0x5c000
	s_nop 0
	v_addc_co_u32_e32 v43, vcc, 0, v41, vcc
	global_load_dword v36, v[36:37], off nt
	s_nop 0
	global_load_dword v37, v[42:43], off nt
	v_add_co_u32_e32 v42, vcc, s6, v40
	s_mov_b32 s6, 0x5e000
	s_nop 0
	v_addc_co_u32_e32 v43, vcc, 0, v41, vcc
	v_add_co_u32_e32 v50, vcc, s6, v40
	s_mov_b32 s6, 0x60000
	s_nop 0
	v_addc_co_u32_e32 v51, vcc, 0, v41, vcc
	global_load_dword v42, v[42:43], off nt
	s_nop 0
	global_load_dword v43, v[50:51], off nt
	v_add_co_u32_e32 v50, vcc, s6, v40
	s_mov_b32 s6, 0x62000
	s_nop 0
	v_addc_co_u32_e32 v51, vcc, 0, v41, vcc
	v_add_co_u32_e32 v52, vcc, s6, v40
	s_mov_b32 s6, 0x64000
	s_nop 0
	v_addc_co_u32_e32 v53, vcc, 0, v41, vcc
	global_load_dword v50, v[50:51], off nt
	s_nop 0
	global_load_dword v51, v[52:53], off nt
	v_add_co_u32_e32 v52, vcc, s6, v40
	s_mov_b32 s6, 0x66000
	s_nop 0
	v_addc_co_u32_e32 v53, vcc, 0, v41, vcc
	v_add_co_u32_e32 v54, vcc, s6, v40
	s_mov_b32 s6, 0x68000
	s_nop 0
	v_addc_co_u32_e32 v55, vcc, 0, v41, vcc
	global_load_dword v52, v[52:53], off nt
	s_nop 0
	global_load_dword v53, v[54:55], off nt
	v_add_co_u32_e32 v54, vcc, s6, v40
	s_mov_b32 s6, 0x6a000
	s_nop 0
	v_addc_co_u32_e32 v55, vcc, 0, v41, vcc
	v_add_co_u32_e32 v56, vcc, s6, v40
	s_mov_b32 s6, 0x6c000
	s_nop 0
	v_addc_co_u32_e32 v57, vcc, 0, v41, vcc
	global_load_dword v54, v[54:55], off nt
	s_nop 0
	global_load_dword v55, v[56:57], off nt
	v_add_co_u32_e32 v56, vcc, s6, v40
	s_mov_b32 s6, 0x6e000
	s_nop 0
	v_addc_co_u32_e32 v57, vcc, 0, v41, vcc
	v_add_co_u32_e32 v58, vcc, s6, v40
	s_mov_b32 s6, 0x70000
	s_nop 0
	v_addc_co_u32_e32 v59, vcc, 0, v41, vcc
	global_load_dword v56, v[56:57], off nt
	s_nop 0
	global_load_dword v57, v[58:59], off nt
	v_add_co_u32_e32 v58, vcc, s6, v40
	s_mov_b32 s6, 0x72000
	s_nop 0
	v_addc_co_u32_e32 v59, vcc, 0, v41, vcc
	v_add_co_u32_e32 v60, vcc, s6, v40
	s_mov_b32 s6, 0x74000
	s_nop 0
	v_addc_co_u32_e32 v61, vcc, 0, v41, vcc
	global_load_dword v58, v[58:59], off nt
	s_nop 0
	global_load_dword v59, v[60:61], off nt
	v_add_co_u32_e32 v60, vcc, s6, v40
	s_mov_b32 s6, 0x76000
	s_nop 0
	v_addc_co_u32_e32 v61, vcc, 0, v41, vcc
	v_add_co_u32_e32 v62, vcc, s6, v40
	s_mov_b32 s6, 0x78000
	s_nop 0
	v_addc_co_u32_e32 v63, vcc, 0, v41, vcc
	global_load_dword v60, v[60:61], off nt
	s_nop 0
	global_load_dword v61, v[62:63], off nt
	v_add_co_u32_e32 v62, vcc, s6, v40
	s_mov_b32 s6, 0x7a000
	s_nop 0
	v_addc_co_u32_e32 v63, vcc, 0, v41, vcc
	v_add_co_u32_e32 v64, vcc, s6, v40
	s_mov_b32 s6, 0x7c000
	s_nop 0
	v_addc_co_u32_e32 v65, vcc, 0, v41, vcc
	global_load_dword v62, v[62:63], off nt
	s_nop 0
	global_load_dword v63, v[64:65], off nt
	v_add_co_u32_e32 v64, vcc, s6, v40
	s_mov_b32 s6, 0x7e000
	s_nop 0
	v_addc_co_u32_e32 v65, vcc, 0, v41, vcc
	v_add_co_u32_e32 v40, vcc, s6, v40
	global_load_dword v64, v[64:65], off nt
	s_nop 0
	v_addc_co_u32_e32 v41, vcc, 0, v41, vcc
	global_load_dword v65, v[40:41], off nt
	s_mov_b64 s[6:7], 0
	global_store_dwordx4 v[38:39], v[44:47], off
